# NORM rows rebalanced: workgroups that also run an AUX unit take 11 rows per wave, the others 26-27
# speedup vs baseline: 1.0060x; 1.0060x over previous
; __device__ __forceinline__ void norm_phase(const float* xs, const float* cs, const float* g, const float* modl, int which, bf16_t* A1, int nrows, int tid) {
;     const int lane = tid & 63, wave = tid >> 6;
;     f32x4 gvv[4];
; #pragma unroll
;     for (int j = 0; j < 4; ++j) gvv[j] = *(const f32x4*)(g + 4 * lane + 256 * j);
;     for (int row = blockIdx.x * 8 + wave; row < nrows; row += gridDim.x * 8) {
;         const float* src = row < MX ? xs + (size_t)row * DM : cs + (size_t)(row - MX) * DM;
;         const int bp = row < MX ? (row >> 12) : 8;
;         const float* sh = modl + (size_t)bp * 6144 + which * 3 * 1024; const float* scl = sh + 1024;
.LBB0_144:
	s_mul_i32 s0, s82, 0x36000
	s_add_u32 s0, s34, s0
	s_addc_u32 s1, s35, 0
	v_writelane_b32 v253, s0, 41
	s_mov_b32 s12, s59
	s_mov_b64 s[10:11], s[62:63]
	v_writelane_b32 v253, s1, 42
	v_readlane_b32 s52, v252, 2
	v_writelane_b32 v253, s4, 43
	s_and_b64 vcc, s[4:5], exec
	v_readlane_b32 s53, v252, 3
	v_writelane_b32 v253, s5, 44
	s_cselect_b32 s1, s53, s87
	s_cselect_b32 s0, s52, s86
	v_writelane_b32 v253, s0, 45
	v_readlane_b32 s56, v252, 6
	v_readlane_b32 s57, v252, 7
	v_writelane_b32 v253, s1, 46
	v_readlane_b32 s0, v252, 25
	v_readlane_b32 s1, v252, 26
	s_cselect_b32 s1, s57, s1
	s_cselect_b32 s0, s56, s0
	v_writelane_b32 v253, s0, 47
	v_readlane_b32 s54, v252, 4
	v_readlane_b32 s55, v252, 5
	v_writelane_b32 v253, s1, 48
	v_readlane_b32 s58, v252, 8
	v_readlane_b32 s59, v252, 9
	v_readlane_b32 s60, v252, 10
	v_readlane_b32 s61, v252, 11
	v_readlane_b32 s62, v252, 12
	v_readlane_b32 s63, v252, 13
	v_readlane_b32 s64, v252, 14
	v_readlane_b32 s65, v252, 15
	v_readlane_b32 s66, v252, 16
	v_readlane_b32 s67, v252, 17
	s_cbranch_vccz .LBB0_152
	v_readlane_b32 s0, v252, 29
	v_ashrrev_i32_e32 v0, 6, v144
	s_nop 0
	v_add_u32_e32 v16, s0, v0
	v_mov_b32_e32 v71, 0x4e0
	v_mov_b32_e32 v120, 0x35a0
	s_cmpk_lt_u32 s0, 0x4e0
	s_cbranch_scc1 .Lnorm_auxwg
	v_add_u32_e32 v16, 0x30c0, v16
	v_mov_b32_e32 v71, 0x320
	v_mov_b32_e32 v120, 0x8800
.Lnorm_auxwg:
	s_mov_b32 s0, 0x8800
	v_cmp_gt_i32_e32 vcc, s0, v16
	s_and_saveexec_b64 s[0:1], vcc
	v_readlane_b32 s66, v253, 27
	v_readlane_b32 s64, v253, 43
	v_readlane_b32 s2, v252, 18
	s_mov_b64 s[62:63], s[10:11]
	s_mov_b32 s59, s12
	v_readlane_b32 s67, v253, 28
	v_readlane_b32 s65, v253, 44
	s_cbranch_execz .LBB0_153
	v_lshlrev_b32_e32 v0, 2, v144
	v_and_b32_e32 v20, 0xfc, v0
	v_readlane_b32 s52, v252, 2
	v_lshlrev_b32_e32 v12, 2, v20
	v_readlane_b32 s64, v252, 14
	v_readlane_b32 s65, v252, 15
	s_waitcnt lgkmcnt(0)
	s_nop 3
	global_load_dwordx4 v[0:3], v12, s[64:65]
	global_load_dwordx4 v[4:7], v12, s[64:65] offset:1024
	global_load_dwordx4 v[8:11], v12, s[64:65] offset:2048
	s_nop 0
	global_load_dwordx4 v[12:15], v12, s[64:65] offset:3072
	v_xor_b32_e32 v17, 1, v223
	v_cmp_lt_i32_e32 vcc, v17, v224
	v_readlane_b32 s66, v252, 16
	v_readlane_b32 s67, v252, 17
	v_cndmask_b32_e32 v17, v223, v17, vcc
	v_cmp_lt_i32_e32 vcc, v228, v224
	v_lshlrev_b32_e32 v24, 2, v17
	v_readlane_b32 s4, v255, 24
	v_cndmask_b32_e32 v17, v223, v228, vcc
	v_cmp_lt_i32_e32 vcc, v225, v224
	v_lshlrev_b32_e32 v25, 2, v17
	v_readlane_b32 s59, v252, 9
	v_cndmask_b32_e32 v17, v223, v225, vcc
	v_lshlrev_b32_e32 v26, 2, v17
	v_xor_b32_e32 v17, 8, v223
	v_cmp_lt_i32_e32 vcc, v17, v224
	v_readlane_b32 s62, v252, 12
	v_readlane_b32 s63, v252, 13
	v_cndmask_b32_e32 v17, v223, v17, vcc
	v_cmp_lt_i32_e32 vcc, v229, v224
	v_lshlrev_b32_e32 v27, 2, v17
	v_readlane_b32 s66, v253, 27
	v_cndmask_b32_e32 v17, v223, v229, vcc
	v_cmp_lt_i32_e32 vcc, v230, v224
	v_readlane_b32 s64, v253, 43
	v_lshlrev_b32_e32 v28, 2, v17
	v_cndmask_b32_e32 v17, v223, v230, vcc
	v_lshlrev_b32_e32 v186, 1, v20
	v_readlane_b32 s5, v255, 25
	s_mov_b32 s59, s12
	s_mov_b64 s[62:63], s[10:11]
	v_readlane_b32 s2, v252, 18
	v_readlane_b32 s67, v253, 28
	v_readlane_b32 s65, v253, 44
	v_lshlrev_b32_e32 v29, 2, v17
	v_lshl_add_u64 v[18:19], s[4:5], 0, v[186:187]
	s_mov_b64 s[4:5], 0
	v_lshlrev_b32_e32 v20, 2, v20
	v_mov_b32_e32 v21, v187
	v_readlane_b32 s53, v252, 3
	v_readlane_b32 s54, v252, 4
	v_readlane_b32 s55, v252, 5
	v_readlane_b32 s56, v252, 6
	v_readlane_b32 s57, v252, 7
	v_readlane_b32 s58, v252, 8
	v_readlane_b32 s60, v252, 10
	v_readlane_b32 s61, v252, 11
	s_branch .LBB0_148
; __device__ __forceinline__ unsigned pk2(float lo, float hi) { f32x2v v = {lo, hi}; bf16x2v b = __builtin_convertvector(v, bf16x2v); return __builtin_bit_cast(unsigned, b); }
; __device__ __forceinline__ void norm_phase(const float* xs, const float* cs, const float* g, const float* modl, int which, bf16_t* A1, int nrows, int tid) {
;     ...
;     for (int row = blockIdx.x * 8 + wave; row < nrows; row += gridDim.x * 8) {
;         const float* src = row < MX ? xs + (size_t)row * DM : cs + (size_t)(row - MX) * DM;
;         const int bp = row < MX ? (row >> 12) : 8;
;         const float* sh = modl + (size_t)bp * 6144 + which * 3 * 1024; const float* scl = sh + 1024;
;         f32x4 v[4]; float ss = 0.f;
; #pragma unroll
;         for (int j = 0; j < 4; ++j) { v[j] = __builtin_nontemporal_load((const f32x4*)(src + 4 * lane + 256 * j)); ss += (v[j][0] * v[j][0] + v[j][1] * v[j][1]) + (v[j][2] * v[j][2] + v[j][3] * v[j][3]); }
;         const float r = rsqrtf(wave_sum(ss) * (1.0f / 1024.0f) + 1e-6f);
; #pragma unroll
;         for (int j = 0; j < 4; ++j) {
;             const f32x4 s1 = *(const f32x4*)(scl + 4 * lane + 256 * j), s0 = *(const f32x4*)(sh + 4 * lane + 256 * j);
;             f32x4 y = v[j] * r * gvv[j]; y = y * (s1 + 1.0f) + s0;
;             *(u32x2*)(A1 + (size_t)row * DM + 4 * lane + 256 * j) = (u32x2){pk2(y[0], y[1]), pk2(y[2], y[3])};
;         }
.LBB0_147:
	s_or_b64 exec, exec, s[6:7]
	v_lshl_add_u64 v[22:23], v[22:23], 0, v[20:21]
	global_load_dwordx4 v[30:33], v[22:23], off nt
	global_load_dwordx4 v[34:37], v[22:23], off offset:1024 nt
	global_load_dwordx4 v[38:41], v[22:23], off offset:3072 nt
	global_load_dwordx4 v[42:45], v[22:23], off offset:2048 nt
	v_min_i32_e32 v22, 0x8000, v16
	v_ashrrev_i32_e32 v22, 12, v22
	v_readlane_b32 s6, v253, 41
	v_mul_hi_i32_i24_e32 v23, 0x6000, v22
	v_mul_i32_i24_e32 v22, 0x6000, v22
	v_readlane_b32 s7, v253, 42
	s_nop 1
	v_lshl_add_u64 v[22:23], s[6:7], 0, v[22:23]
	v_lshl_add_u64 v[22:23], v[22:23], 0, v[20:21]
	s_mov_b64 s[6:7], 0x1000
	v_lshl_add_u64 v[56:57], v[22:23], 0, s[6:7]
	global_load_dwordx4 v[72:75], v[56:57], off
	global_load_dwordx4 v[88:91], v[22:23], off
	global_load_dwordx4 v[76:79], v[56:57], off offset:1024
	global_load_dwordx4 v[92:95], v[22:23], off offset:1024
	global_load_dwordx4 v[80:83], v[56:57], off offset:2048
	global_load_dwordx4 v[96:99], v[22:23], off offset:2048
	global_load_dwordx4 v[84:87], v[56:57], off offset:3072
	global_load_dwordx4 v[100:103], v[22:23], off offset:3072
	s_waitcnt vmcnt(8)
	v_pk_mul_f32 v[54:55], v[32:33], v[32:33]
	v_pk_mul_f32 v[56:57], v[30:31], v[30:31]
	s_nop 0
	s_nop 0
	v_pk_mul_f32 v[58:59], v[36:37], v[36:37]
	v_pk_mul_f32 v[60:61], v[34:35], v[34:35]
	v_pk_mov_b32 v[66:67], v[56:57], v[54:55] op_sel:[1,0]
	v_mov_b32_e32 v57, v55
	v_pk_mov_b32 v[54:55], v[60:61], v[58:59] op_sel:[1,0]
	v_mov_b32_e32 v61, v59
	v_mul_f32_e32 v65, v38, v38
	v_mul_f32_e32 v62, v43, v43
	v_mul_f32_e32 v64, v45, v45
	v_pk_add_f32 v[56:57], v[66:67], v[56:57]
	v_pk_add_f32 v[54:55], v[54:55], v[60:61]
	v_mul_f32_e32 v68, v39, v39
	v_mul_f32_e32 v69, v40, v40
	v_mul_f32_e32 v70, v41, v41
	v_pk_fma_f32 v[58:59], v[42:43], v[42:43], v[62:63] op_sel_hi:[1,1,0]
	v_pk_fma_f32 v[62:63], v[44:45], v[44:45], v[64:65] op_sel_hi:[1,1,0]
	v_pk_add_f32 v[56:57], v[56:57], v[56:57] op_sel:[0,1] op_sel_hi:[1,0]
	v_pk_add_f32 v[54:55], v[54:55], v[54:55] op_sel:[0,1] op_sel_hi:[1,0]
	v_mov_b32_e32 v59, v69
	v_mov_b32_e32 v63, v70
	v_mov_b32_e32 v57, v65
	v_mov_b32_e32 v55, v68
	v_pk_add_f32 v[58:59], v[58:59], v[62:63]
	v_pk_add_f32 v[54:55], v[56:57], v[54:55]
	v_pk_add_f32 v[54:55], v[54:55], v[58:59]
	v_add_f32_e32 v54, v54, v55
	ds_bpermute_b32 v55, v24, v54
	s_waitcnt lgkmcnt(0)
	v_add_f32_e32 v54, v54, v55
	ds_bpermute_b32 v55, v25, v54
	s_waitcnt lgkmcnt(0)
	v_add_f32_e32 v54, v54, v55
	ds_bpermute_b32 v55, v26, v54
	s_waitcnt lgkmcnt(0)
	v_add_f32_e32 v54, v54, v55
	ds_bpermute_b32 v55, v27, v54
	s_waitcnt lgkmcnt(0)
	v_add_f32_e32 v54, v54, v55
	ds_bpermute_b32 v55, v28, v54
	s_waitcnt lgkmcnt(0)
	v_add_f32_e32 v56, v54, v55
	ds_bpermute_b32 v57, v29, v56
	v_lshlrev_b64 v[54:55], 11, v[16:17]
	v_lshl_add_u64 v[54:55], v[18:19], 0, v[54:55]
	v_add_u32_e32 v16, v71, v16
	s_waitcnt lgkmcnt(0)
	v_add_f32_e32 v17, v56, v57
	v_fmamk_f32 v17, v17, 0x3a800000, v221
	v_mul_f32_e32 v56, 0x4b800000, v17
	v_cmp_gt_f32_e32 vcc, s16, v17
	s_nop 1
	v_cndmask_b32_e32 v17, v17, v56, vcc
	v_rsq_f32_e32 v17, v17
	v_mul_f32_e32 v58, 0x45800000, v17
	v_cndmask_b32_e32 v58, v17, v58, vcc
	v_cmp_le_i32_e32 vcc, v120, v16
	s_or_b64 s[4:5], vcc, s[4:5]
	s_waitcnt vmcnt(0)
	v_pk_mul_f32 v[32:33], v[32:33], v[58:59] op_sel_hi:[1,0]
	v_pk_mul_f32 v[30:31], v[30:31], v[58:59] op_sel_hi:[1,0]
	v_pk_mul_f32 v[32:33], v[2:3], v[32:33]
	v_pk_mul_f32 v[30:31], v[0:1], v[30:31]
	v_pk_add_f32 v[74:75], v[74:75], 1.0 op_sel_hi:[1,0]
	v_pk_add_f32 v[72:73], v[72:73], 1.0 op_sel_hi:[1,0]
	v_pk_fma_f32 v[32:33], v[74:75], v[32:33], v[90:91]
	v_pk_fma_f32 v[30:31], v[72:73], v[30:31], v[88:89]
	s_nop 0
	v_cvt_pk_bf16_f32 v30, v30, v31
	v_cvt_pk_bf16_f32 v31, v32, v33
	global_store_dwordx2 v[54:55], v[30:31], off
	v_pk_mul_f32 v[36:37], v[36:37], v[58:59] op_sel_hi:[1,0]
	v_pk_mul_f32 v[34:35], v[34:35], v[58:59] op_sel_hi:[1,0]
	v_pk_mul_f32 v[36:37], v[6:7], v[36:37]
	v_pk_mul_f32 v[34:35], v[4:5], v[34:35]
	v_pk_add_f32 v[78:79], v[78:79], 1.0 op_sel_hi:[1,0]
	v_pk_add_f32 v[76:77], v[76:77], 1.0 op_sel_hi:[1,0]
	v_pk_fma_f32 v[36:37], v[78:79], v[36:37], v[94:95]
	v_pk_fma_f32 v[34:35], v[76:77], v[34:35], v[92:93]
	s_nop 0
	v_cvt_pk_bf16_f32 v34, v34, v35
	v_cvt_pk_bf16_f32 v35, v36, v37
	global_store_dwordx2 v[54:55], v[34:35], off offset:512
	v_pk_mul_f32 v[44:45], v[44:45], v[58:59] op_sel_hi:[1,0]
	v_pk_mul_f32 v[42:43], v[42:43], v[58:59] op_sel_hi:[1,0]
	v_pk_mul_f32 v[44:45], v[10:11], v[44:45]
	v_pk_mul_f32 v[42:43], v[8:9], v[42:43]
	v_pk_add_f32 v[82:83], v[82:83], 1.0 op_sel_hi:[1,0]
	v_pk_add_f32 v[80:81], v[80:81], 1.0 op_sel_hi:[1,0]
	v_pk_fma_f32 v[44:45], v[82:83], v[44:45], v[98:99]
	v_pk_fma_f32 v[42:43], v[80:81], v[42:43], v[96:97]
	s_nop 0
	v_cvt_pk_bf16_f32 v42, v42, v43
	v_cvt_pk_bf16_f32 v43, v44, v45
	global_store_dwordx2 v[54:55], v[42:43], off offset:1024
	v_pk_mul_f32 v[40:41], v[40:41], v[58:59] op_sel_hi:[1,0]
	v_pk_mul_f32 v[38:39], v[38:39], v[58:59] op_sel_hi:[1,0]
	v_pk_mul_f32 v[40:41], v[14:15], v[40:41]
	v_pk_mul_f32 v[38:39], v[12:13], v[38:39]
	v_pk_add_f32 v[86:87], v[86:87], 1.0 op_sel_hi:[1,0]
	v_pk_add_f32 v[84:85], v[84:85], 1.0 op_sel_hi:[1,0]
	v_pk_fma_f32 v[40:41], v[86:87], v[40:41], v[102:103]
	v_pk_fma_f32 v[38:39], v[84:85], v[38:39], v[100:101]
	s_nop 0
	v_cvt_pk_bf16_f32 v38, v38, v39
	v_cvt_pk_bf16_f32 v39, v40, v41
	global_store_dwordx2 v[54:55], v[38:39], off offset:1536
	s_andn2_b64 exec, exec, s[4:5]
	s_cbranch_execz .LBB0_153
